# NSA compressed and window loops: leading K-fragment LDS reads issued directly after the barrier, ahead of the next tile's global loads
# speedup vs baseline: 1.0004x; 1.0004x over previous
.LBB0_1562:
	s_bitcmp1_b32 s7, 0
	s_cselect_b32 s11, 0x2400, 0
	s_add_i32 s11, s11, 0
	v_add3_u32 v10, s11, v105, v92
	s_cmp_ge_i32 s7, s8
	s_waitcnt vmcnt(0)
	ds_write_b128 v10, v[2:5]
	ds_write_b128 v10, v[6:9] offset:18432
	s_waitcnt lgkmcnt(0)
	s_barrier
	v_add3_u32 v80, s11, v106, v107
	ds_read_b128 v[10:13], v80
	ds_read_b128 v[220:223], v80 offset:4608
	ds_read_b128 v[240:243], v80 offset:32
	ds_read_b128 v[244:247], v80 offset:4640
	ds_read_b128 v[248:251], v80 offset:64
	s_cbranch_scc1 .LBB0_1564
	global_load_dwordx4 v[2:5], v[94:95], off
	global_load_dwordx4 v[6:9], v[96:97], off
.LBB0_1564:
	v_xor_b32_e32 v48, 0x80000000, v93
	v_mov_b32_e32 v49, v48
	v_mov_b32_e32 v50, v48
	v_mov_b32_e32 v51, v48
	v_mov_b32_e32 v52, v48
	v_mov_b32_e32 v53, v48
	v_mov_b32_e32 v54, v48
	v_mov_b32_e32 v55, v48
	v_mov_b32_e32 v56, v48
	v_mov_b32_e32 v57, v48
	v_mov_b32_e32 v58, v48
	v_mov_b32_e32 v59, v48
	v_mov_b32_e32 v60, v48
	v_mov_b32_e32 v61, v48
	v_mov_b32_e32 v62, v48
	v_mov_b32_e32 v63, v48
	s_cmp_le_i32 s10, s9
	s_waitcnt lgkmcnt(4)
	v_mfma_f32_32x32x16_bf16 v[64:79], v[10:13], v[144:147], v[48:63]
	ds_read_b128 v[10:13], v80 offset:4672
	s_waitcnt lgkmcnt(4)
	v_mfma_f32_32x32x16_bf16 v[48:63], v[220:223], v[144:147], v[48:63]
	ds_read_b128 v[220:223], v80 offset:96
	s_waitcnt lgkmcnt(4)
	v_mfma_f32_32x32x16_bf16 v[64:79], v[240:243], v[148:151], v[64:79]
	ds_read_b128 v[240:243], v80 offset:4704
	s_waitcnt lgkmcnt(4)
	v_mfma_f32_32x32x16_bf16 v[48:63], v[244:247], v[148:151], v[48:63]
	s_waitcnt lgkmcnt(3)
	v_mfma_f32_32x32x16_bf16 v[64:79], v[248:251], v[152:155], v[64:79]
	s_waitcnt lgkmcnt(2)
	v_mfma_f32_32x32x16_bf16 v[48:63], v[10:13], v[152:155], v[48:63]
	s_waitcnt lgkmcnt(1)
	v_mfma_f32_32x32x16_bf16 v[64:79], v[220:223], v[156:159], v[64:79]
	s_waitcnt lgkmcnt(0)
	v_mfma_f32_32x32x16_bf16 v[48:63], v[240:243], v[156:159], v[48:63]
	s_cbranch_scc1 .LBB0_1566
	v_add_u32_e32 v10, s10, v108
	v_cmp_le_i32_e32 vcc, v10, v109
	v_add_u32_e32 v11, 0x21f, v10
	s_nop 4
	v_cndmask_b32_e32 v64, v236, v64, vcc
	v_cmp_le_i32_e32 vcc, v11, v188
	v_add_u32_e32 v11, 16, v10
	s_nop 0
	v_cndmask_b32_e32 v48, v236, v48, vcc
	v_cmp_le_i32_e32 vcc, v11, v109
	v_add_u32_e32 v11, 0x22f, v10
	s_nop 0
	v_cndmask_b32_e32 v65, v236, v65, vcc
	v_cmp_le_i32_e32 vcc, v11, v188
	v_add_u32_e32 v11, 32, v10
	s_nop 0
	v_cndmask_b32_e32 v49, v236, v49, vcc
	v_cmp_le_i32_e32 vcc, v11, v109
	v_add_u32_e32 v11, 0x23f, v10
	s_nop 0
	v_cndmask_b32_e32 v66, v236, v66, vcc
	v_cmp_le_i32_e32 vcc, v11, v188
	v_add_u32_e32 v11, 48, v10
	s_nop 0
	v_cndmask_b32_e32 v50, v236, v50, vcc
	v_cmp_le_i32_e32 vcc, v11, v109
	v_add_u32_e32 v11, 0x80, v10
	s_nop 0
	v_cndmask_b32_e32 v67, v236, v67, vcc
	v_cmp_le_i32_e32 vcc, v10, v112
	s_nop 1
	v_cndmask_b32_e32 v51, v236, v51, vcc
	v_cmp_le_i32_e32 vcc, v11, v109
	v_add_u32_e32 v11, 0x29f, v10
	s_nop 0
	v_cndmask_b32_e32 v68, v236, v68, vcc
	v_cmp_le_i32_e32 vcc, v11, v188
	v_add_u32_e32 v11, 0x90, v10
	s_nop 0
	v_cndmask_b32_e32 v52, v236, v52, vcc
	v_cmp_le_i32_e32 vcc, v11, v109
	v_add_u32_e32 v11, 0x2af, v10
	s_nop 0
	v_cndmask_b32_e32 v69, v236, v69, vcc
	v_cmp_le_i32_e32 vcc, v11, v188
	v_add_u32_e32 v11, 0xa0, v10
	s_nop 0
	v_cndmask_b32_e32 v53, v236, v53, vcc
	v_cmp_le_i32_e32 vcc, v11, v109
	v_add_u32_e32 v11, 0x2bf, v10
	s_nop 0
	v_cndmask_b32_e32 v70, v236, v70, vcc
	v_cmp_le_i32_e32 vcc, v11, v188
	v_add_u32_e32 v11, 0xb0, v10
	s_nop 0
	v_cndmask_b32_e32 v54, v236, v54, vcc
	v_cmp_le_i32_e32 vcc, v11, v109
	v_add_u32_e32 v11, 0x100, v10
	s_nop 0
	v_cndmask_b32_e32 v71, v236, v71, vcc
	v_cmp_le_i32_e32 vcc, v10, v113
	s_nop 1
	v_cndmask_b32_e32 v55, v236, v55, vcc
	v_cmp_le_i32_e32 vcc, v11, v109
	v_add_u32_e32 v11, 0x31f, v10
	s_nop 0
	v_cndmask_b32_e32 v72, v236, v72, vcc
	v_cmp_le_i32_e32 vcc, v11, v188
	v_add_u32_e32 v11, 0x110, v10
	s_nop 0
	v_cndmask_b32_e32 v56, v236, v56, vcc
	v_cmp_le_i32_e32 vcc, v11, v109
	v_add_u32_e32 v11, 0x32f, v10
	s_nop 0
	v_cndmask_b32_e32 v73, v236, v73, vcc
	v_cmp_le_i32_e32 vcc, v11, v188
	v_add_u32_e32 v11, 0x120, v10
	s_nop 0
	v_cndmask_b32_e32 v57, v236, v57, vcc
	v_cmp_le_i32_e32 vcc, v11, v109
	v_add_u32_e32 v11, 0x33f, v10
	s_nop 0
	v_cndmask_b32_e32 v74, v236, v74, vcc
	v_cmp_le_i32_e32 vcc, v11, v188
	v_add_u32_e32 v11, 0x130, v10
	s_nop 0
	v_cndmask_b32_e32 v58, v236, v58, vcc
	v_cmp_le_i32_e32 vcc, v11, v109
	v_add_u32_e32 v11, 0x180, v10
	s_nop 0
	v_cndmask_b32_e32 v75, v236, v75, vcc
	v_cmp_le_i32_e32 vcc, v10, v114
	s_nop 1
	v_cndmask_b32_e32 v59, v236, v59, vcc
	v_cmp_le_i32_e32 vcc, v11, v109
	v_add_u32_e32 v11, 0x39f, v10
	s_nop 0
	v_cndmask_b32_e32 v76, v236, v76, vcc
	v_cmp_le_i32_e32 vcc, v11, v188
	v_add_u32_e32 v11, 0x190, v10
	s_nop 0
	v_cndmask_b32_e32 v60, v236, v60, vcc
	v_cmp_le_i32_e32 vcc, v11, v109
	v_add_u32_e32 v11, 0x3af, v10
	s_nop 0
	v_cndmask_b32_e32 v77, v236, v77, vcc
	v_cmp_le_i32_e32 vcc, v11, v188
	v_add_u32_e32 v11, 0x1a0, v10
	s_nop 0
	v_cndmask_b32_e32 v61, v236, v61, vcc
	v_cmp_le_i32_e32 vcc, v11, v109
	v_add_u32_e32 v11, 0x3bf, v10
	s_nop 0
	v_cndmask_b32_e32 v78, v236, v78, vcc
	v_cmp_le_i32_e32 vcc, v11, v188
	v_add_u32_e32 v11, 0x1b0, v10
	v_add_u32_e32 v10, 0x3cf, v10
	v_cndmask_b32_e32 v62, v236, v62, vcc
	v_cmp_le_i32_e32 vcc, v11, v109
	s_nop 1
	v_cndmask_b32_e32 v79, v236, v79, vcc
	v_cmp_le_i32_e32 vcc, v10, v188
	s_nop 1
	v_cndmask_b32_e32 v63, v236, v63, vcc

.LBB0_1664:
	s_add_i32 s0, s2, s4
	s_add_i32 s1, s0, -8
	s_bitcmp1_b32 s4, 0
	s_cselect_b32 s5, 0x2400, 0
	s_add_i32 s5, s5, 0
	v_add3_u32 v10, s5, v197, v0
	s_cmp_ge_i32 s1, s76
	s_waitcnt vmcnt(0)
	ds_write_b128 v10, v[6:9]
	ds_write_b128 v10, v[2:5] offset:18432
	s_waitcnt lgkmcnt(0)
	s_barrier
	v_add3_u32 v160, s5, v198, v199
	ds_read_b128 v[10:13], v160
	ds_read_b128 v[220:223], v160 offset:4608
	ds_read_b128 v[240:243], v160 offset:32
	ds_read_b128 v[244:247], v160 offset:4640
	ds_read_b128 v[248:251], v160 offset:64
	s_cbranch_scc1 .LBB0_1666
	s_add_i32 s6, s0, -7
	v_mad_i64_i32 v[2:3], s[0:1], s6, v230, v[14:15]
	v_mad_i64_i32 v[4:5], s[0:1], s6, v230, v[192:193]
	global_load_dwordx4 v[6:9], v[2:3], off
	s_nop 0
	global_load_dwordx4 v[2:5], v[4:5], off
.LBB0_1666:
	v_xor_b32_e32 v112, 0x80000000, v204
	v_mov_b32_e32 v113, v112
	v_mov_b32_e32 v114, v112
	v_mov_b32_e32 v115, v112
	v_mov_b32_e32 v116, v112
	v_mov_b32_e32 v117, v112
	v_mov_b32_e32 v118, v112
	v_mov_b32_e32 v119, v112
	v_mov_b32_e32 v120, v112
	v_mov_b32_e32 v121, v112
	v_mov_b32_e32 v122, v112
	v_mov_b32_e32 v123, v112
	v_mov_b32_e32 v124, v112
	v_mov_b32_e32 v125, v112
	v_mov_b32_e32 v126, v112
	v_mov_b32_e32 v127, v112
	s_add_i32 s6, s3, s4
	s_cmp_eq_u32 s6, 11
	s_waitcnt lgkmcnt(4)
	v_mfma_f32_32x32x16_bf16 v[128:143], v[10:13], v[144:147], v[112:127]
	ds_read_b128 v[10:13], v160 offset:4672
	s_cselect_b64 s[0:1], -1, 0
	s_cmp_eq_u32 s6, 3
	s_cselect_b64 s[6:7], -1, 0
	s_or_b64 s[0:1], s[0:1], s[6:7]
	s_andn2_b64 vcc, exec, s[0:1]
	s_waitcnt lgkmcnt(4)
	v_mfma_f32_32x32x16_bf16 v[112:127], v[220:223], v[144:147], v[112:127]
	ds_read_b128 v[220:223], v160 offset:96
	s_waitcnt lgkmcnt(4)
	v_mfma_f32_32x32x16_bf16 v[128:143], v[240:243], v[148:151], v[128:143]
	ds_read_b128 v[240:243], v160 offset:4704
	s_waitcnt lgkmcnt(4)
	v_mfma_f32_32x32x16_bf16 v[112:127], v[244:247], v[148:151], v[112:127]
	s_waitcnt lgkmcnt(3)
	v_mfma_f32_32x32x16_bf16 v[128:143], v[248:251], v[152:155], v[128:143]
	s_waitcnt lgkmcnt(2)
	v_mfma_f32_32x32x16_bf16 v[112:127], v[10:13], v[152:155], v[112:127]
	s_waitcnt lgkmcnt(1)
	v_mfma_f32_32x32x16_bf16 v[128:143], v[220:223], v[156:159], v[128:143]
	s_waitcnt lgkmcnt(0)
	v_mfma_f32_32x32x16_bf16 v[112:127], v[240:243], v[156:159], v[112:127]
	s_cbranch_vccnz .LBB0_1668
	v_cmp_gt_i32_e32 vcc, v203, v188
	v_cmp_lt_i32_e64 s[0:1], v203, v200
	s_or_b64 vcc, vcc, s[0:1]
	v_add_u32_e32 v10, 32, v203
	s_nop 4
	v_cndmask_b32_e32 v128, v128, v236, vcc
	v_cmp_gt_i32_e32 vcc, v10, v188
	v_cmp_lt_i32_e64 s[0:1], v10, v200
	s_or_b64 vcc, vcc, s[0:1]
	v_add_u32_e32 v10, 1, v203
	v_cndmask_b32_e32 v112, v112, v236, vcc
	v_cmp_ge_i32_e32 vcc, v203, v188
	v_cmp_lt_i32_e64 s[0:1], v10, v200
	s_or_b64 vcc, vcc, s[0:1]
	v_add_u32_e32 v10, 33, v203
	v_cndmask_b32_e32 v129, v129, v236, vcc
	v_cmp_gt_i32_e32 vcc, v10, v188
	v_cmp_lt_i32_e64 s[0:1], v10, v200
	s_or_b64 vcc, vcc, s[0:1]
	v_add_u32_e32 v10, 2, v203
	v_cndmask_b32_e32 v113, v113, v236, vcc
	v_cmp_gt_i32_e32 vcc, v10, v188
	v_cmp_lt_i32_e64 s[0:1], v10, v200
	s_or_b64 vcc, vcc, s[0:1]
	v_add_u32_e32 v10, 34, v203
	v_cndmask_b32_e32 v130, v130, v236, vcc
	v_cmp_gt_i32_e32 vcc, v10, v188
	v_cmp_lt_i32_e64 s[0:1], v10, v200
	s_or_b64 vcc, vcc, s[0:1]
	v_add_u32_e32 v10, 3, v203
	v_cndmask_b32_e32 v114, v114, v236, vcc
	v_cmp_gt_i32_e32 vcc, v10, v188
	v_cmp_lt_i32_e64 s[0:1], v10, v200
	s_or_b64 vcc, vcc, s[0:1]
	v_add_u32_e32 v10, 35, v203
	v_cndmask_b32_e32 v131, v131, v236, vcc
	v_cmp_gt_i32_e32 vcc, v10, v188
	v_cmp_lt_i32_e64 s[0:1], v10, v200
	s_or_b64 vcc, vcc, s[0:1]
	v_add_u32_e32 v10, 8, v203
	v_cndmask_b32_e32 v115, v115, v236, vcc
	v_cmp_gt_i32_e32 vcc, v10, v188
	v_cmp_lt_i32_e64 s[0:1], v10, v200
	s_or_b64 vcc, vcc, s[0:1]
	v_add_u32_e32 v10, 40, v203
	v_cndmask_b32_e32 v132, v132, v236, vcc
	v_cmp_gt_i32_e32 vcc, v10, v188
	v_cmp_lt_i32_e64 s[0:1], v10, v200
	s_or_b64 vcc, vcc, s[0:1]
	v_add_u32_e32 v10, 9, v203
	v_cndmask_b32_e32 v116, v116, v236, vcc
	v_cmp_gt_i32_e32 vcc, v10, v188
	v_cmp_lt_i32_e64 s[0:1], v10, v200
	s_or_b64 vcc, vcc, s[0:1]
	v_add_u32_e32 v10, 41, v203
	v_cndmask_b32_e32 v133, v133, v236, vcc
	v_cmp_gt_i32_e32 vcc, v10, v188
	v_cmp_lt_i32_e64 s[0:1], v10, v200
	s_or_b64 vcc, vcc, s[0:1]
	v_add_u32_e32 v10, 10, v203
	v_cndmask_b32_e32 v117, v117, v236, vcc
	v_cmp_gt_i32_e32 vcc, v10, v188
	v_cmp_lt_i32_e64 s[0:1], v10, v200
	s_or_b64 vcc, vcc, s[0:1]
	v_add_u32_e32 v10, 42, v203
	v_cndmask_b32_e32 v134, v134, v236, vcc
	v_cmp_gt_i32_e32 vcc, v10, v188
	v_cmp_lt_i32_e64 s[0:1], v10, v200
	s_or_b64 vcc, vcc, s[0:1]
	v_add_u32_e32 v10, 11, v203
	v_cndmask_b32_e32 v118, v118, v236, vcc
	v_cmp_gt_i32_e32 vcc, v10, v188
	v_cmp_lt_i32_e64 s[0:1], v10, v200
	s_or_b64 vcc, vcc, s[0:1]
	v_add_u32_e32 v10, 43, v203
	v_cndmask_b32_e32 v135, v135, v236, vcc
	v_cmp_gt_i32_e32 vcc, v10, v188
	v_cmp_lt_i32_e64 s[0:1], v10, v200
	s_or_b64 vcc, vcc, s[0:1]
	v_add_u32_e32 v10, 16, v203
	v_cndmask_b32_e32 v119, v119, v236, vcc
	v_cmp_gt_i32_e32 vcc, v10, v188
	v_cmp_lt_i32_e64 s[0:1], v10, v200
	s_or_b64 vcc, vcc, s[0:1]
	v_add_u32_e32 v10, 48, v203
	v_cndmask_b32_e32 v136, v136, v236, vcc
	v_cmp_gt_i32_e32 vcc, v10, v188
	v_cmp_lt_i32_e64 s[0:1], v10, v200
	s_or_b64 vcc, vcc, s[0:1]
	v_add_u32_e32 v10, 17, v203
	v_cndmask_b32_e32 v120, v120, v236, vcc
	v_cmp_gt_i32_e32 vcc, v10, v188
	v_cmp_lt_i32_e64 s[0:1], v10, v200
	s_or_b64 vcc, vcc, s[0:1]
	v_add_u32_e32 v10, 49, v203
	v_cndmask_b32_e32 v137, v137, v236, vcc
	v_cmp_gt_i32_e32 vcc, v10, v188
	v_cmp_lt_i32_e64 s[0:1], v10, v200
	s_or_b64 vcc, vcc, s[0:1]
	v_add_u32_e32 v10, 18, v203
	v_cndmask_b32_e32 v121, v121, v236, vcc
	v_cmp_gt_i32_e32 vcc, v10, v188
	v_cmp_lt_i32_e64 s[0:1], v10, v200
	s_or_b64 vcc, vcc, s[0:1]
	v_add_u32_e32 v10, 50, v203
	v_cndmask_b32_e32 v138, v138, v236, vcc
	v_cmp_gt_i32_e32 vcc, v10, v188
	v_cmp_lt_i32_e64 s[0:1], v10, v200
	s_or_b64 vcc, vcc, s[0:1]
	v_add_u32_e32 v10, 19, v203
	v_cndmask_b32_e32 v122, v122, v236, vcc
	v_cmp_gt_i32_e32 vcc, v10, v188
	v_cmp_lt_i32_e64 s[0:1], v10, v200
	s_or_b64 vcc, vcc, s[0:1]
	v_add_u32_e32 v10, 51, v203
	v_cndmask_b32_e32 v139, v139, v236, vcc
	v_cmp_gt_i32_e32 vcc, v10, v188
	v_cmp_lt_i32_e64 s[0:1], v10, v200
	s_or_b64 vcc, vcc, s[0:1]
	v_add_u32_e32 v10, 24, v203
	v_cndmask_b32_e32 v123, v123, v236, vcc
	v_cmp_gt_i32_e32 vcc, v10, v188
	v_cmp_lt_i32_e64 s[0:1], v10, v200
	s_or_b64 vcc, vcc, s[0:1]
	v_add_u32_e32 v10, 56, v203
	v_cndmask_b32_e32 v140, v140, v236, vcc
	v_cmp_gt_i32_e32 vcc, v10, v188
	v_cmp_lt_i32_e64 s[0:1], v10, v200
	s_or_b64 vcc, vcc, s[0:1]
	v_add_u32_e32 v10, 25, v203
	v_cndmask_b32_e32 v124, v124, v236, vcc
	v_cmp_gt_i32_e32 vcc, v10, v188
	v_cmp_lt_i32_e64 s[0:1], v10, v200
	s_or_b64 vcc, vcc, s[0:1]
	v_add_u32_e32 v10, 57, v203
	v_cndmask_b32_e32 v141, v141, v236, vcc
	v_cmp_gt_i32_e32 vcc, v10, v188
	v_cmp_lt_i32_e64 s[0:1], v10, v200
	s_or_b64 vcc, vcc, s[0:1]
	v_add_u32_e32 v10, 26, v203
	v_cndmask_b32_e32 v125, v125, v236, vcc
	v_cmp_gt_i32_e32 vcc, v10, v188
	v_cmp_lt_i32_e64 s[0:1], v10, v200
	s_or_b64 vcc, vcc, s[0:1]
	v_add_u32_e32 v10, 58, v203
	v_cndmask_b32_e32 v142, v142, v236, vcc
	v_cmp_gt_i32_e32 vcc, v10, v188
	v_cmp_lt_i32_e64 s[0:1], v10, v200
	s_or_b64 vcc, vcc, s[0:1]
	v_add_u32_e32 v10, 27, v203
	v_cndmask_b32_e32 v126, v126, v236, vcc
	v_cmp_gt_i32_e32 vcc, v10, v188
	v_cmp_lt_i32_e64 s[0:1], v10, v200
	s_or_b64 vcc, vcc, s[0:1]
	v_add_u32_e32 v10, 59, v203
	v_cndmask_b32_e32 v143, v143, v236, vcc
	v_cmp_gt_i32_e32 vcc, v10, v188
	v_cmp_lt_i32_e64 s[0:1], v10, v200
	s_or_b64 vcc, vcc, s[0:1]
	v_cndmask_b32_e32 v127, v127, v236, vcc
